# hgrn_c: next-unit operand loads spread over the gate/decay VALU stretch instead of one block at the top
# baseline (speedup 1.0000x reference)
; #define LAS __attribute__((address_space(3)))
; __device__ __forceinline__ int crow(int reg, int h) { return (reg & 3) + 8 * (reg >> 2) + 4 * h; }
; #define MFMA32(a, b, c) __builtin_amdgcn_mfma_f32_32x32x16_bf16((a), (b), (c), 0, 0, 0)
; __device__ __forceinline__ void hgrn_c_compute(Ctx& X, int u, const RawC& R) {
;     ...
;     {
;         f32x16 acc;
; #pragma unroll
;         for (int i = 0; i < 16; ++i) acc[i] = 0.f;
; #pragma unroll
;         for (int kk = 0; kk < 8; ++kk) {
;             const bf16x8 af = *(const LAS bf16x8*)(QH + (32 * tt2 + r) * 136 + 16 * kk + 8 * h);
;             acc = MFMA32(af, sfr[kk], acc);
;         }
; #pragma unroll
;         for (int ks = 0; ks < 4; ++ks) {
;             const bf16x8 af = *(const LAS bf16x8*)(AM + (32 * tt2 + r) * 72 + 16 * ks + 8 * h);
;             const bf16x8 bfr = *(const LAS bf16x8*)(VT + (32 * vt2 + r) * 72 + 16 * ks + 8 * h);
;             acc = MFMA32(af, bfr, acc);
;         }
; #pragma unroll
;         for (int i = 0; i < 16; ++i) OF[(32 * tt2 + crow(i, h)) * 132 + 32 * vt2 + r] = acc[i];
;     }
.LBB0_732:
	v_add_u32_e32 v119, v58, v119
	s_waitcnt vmcnt(0) lgkmcnt(0)
	s_barrier
	ds_read_b128 v[52:55], v202
	v_xor_b32_e32 v203, 0x20, v202
	ds_read_b128 v[48:51], v203
	v_xor_b32_e32 v203, 0x40, v202
	ds_read_b128 v[44:47], v203
	v_xor_b32_e32 v203, 0x60, v202
	ds_read_b128 v[40:43], v203
	v_xor_b32_e32 v203, 0x80, v202
	ds_read_b128 v[36:39], v203
	v_xor_b32_e32 v203, 0xa0, v202
	ds_read_b128 v[32:35], v203
	v_xor_b32_e32 v203, 0xc0, v202
	ds_read_b128 v[24:27], v203
	v_xor_b32_e32 v203, 0xe0, v202
	ds_read_b128 v[20:23], v203
	ds_read_b128 v[0:3], v119
	ds_read_b128 v[150:153], v119 offset:32
	s_waitcnt lgkmcnt(1)
	v_mfma_f32_32x32x16_bf16 v[0:15], v[0:3], v[52:55], 0
	v_add_u32_e32 v115, v96, v115
	s_waitcnt vmcnt(1)
	v_lshlrev_b32_e32 v174, 16, v16
	v_and_b32_e32 v175, 0xffff0000, v16
	v_lshlrev_b32_e32 v176, 16, v19
	v_and_b32_e32 v177, 0xffff0000, v19
	v_add_u32_e32 v121, s2, v78
	s_waitcnt vmcnt(0)
	v_lshlrev_b32_e32 v170, 16, v28
	s_waitcnt lgkmcnt(0)
	v_mfma_f32_32x32x16_bf16 v[0:15], v[150:153], v[48:51], v[0:15]
	ds_read_b128 v[48:51], v119 offset:64
	ds_read_b128 v[52:55], v119 offset:96
	v_and_b32_e32 v171, 0xffff0000, v28
	v_lshlrev_b32_e32 v172, 16, v29
	v_and_b32_e32 v173, 0xffff0000, v29
	s_add_i32 s54, s54, s50
	s_add_i32 s36, s36, s40
	v_lshl_add_u64 v[66:67], v[66:67], 0, s[28:29]
	s_waitcnt lgkmcnt(1)
	v_mfma_f32_32x32x16_bf16 v[0:15], v[48:51], v[44:47], v[0:15]
	v_mov_b32_e32 v168, v114
	v_mov_b32_e32 v167, v112
	v_mov_b32_e32 v166, v113
	v_mov_b32_e32 v165, v122
	v_mov_b32_e32 v161, v123
	v_mov_b32_e32 v160, v124
	v_mov_b32_e32 v163, v128
	s_waitcnt lgkmcnt(0)
	v_mfma_f32_32x32x16_bf16 v[0:15], v[52:55], v[40:43], v[0:15]
	ds_read_b128 v[40:43], v119 offset:128
	ds_read_b128 v[44:47], v119 offset:160
	v_mov_b32_e32 v162, v129
	v_mov_b32_e32 v156, v137
	v_mov_b32_e32 v155, v138
	v_mov_b32_e32 v154, v139
	v_mov_b32_e32 v152, v148
	v_mov_b32_e32 v164, v105
	s_waitcnt lgkmcnt(1)
	v_mfma_f32_32x32x16_bf16 v[0:15], v[40:43], v[36:39], v[0:15]
	ds_read_b128 v[36:39], v62 offset:52224
	ds_read_b128 v[40:43], v62 offset:52256
	ds_read_b128 v[48:51], v119 offset:192
	v_mov_b32_e32 v159, v106
	v_mov_b32_e32 v158, v107
	v_mov_b32_e32 v157, v108
	v_mov_b32_e32 v153, v109
	v_mov_b32_e32 v151, v116
	v_mov_b32_e32 v150, v110
	s_waitcnt lgkmcnt(3)
	v_mfma_f32_32x32x16_bf16 v[0:15], v[44:47], v[32:35], v[0:15]
	ds_read_b128 v[32:35], v62 offset:52288
	ds_read_b128 v[44:47], v62 offset:52320
	ds_read_b128 v[52:55], v119 offset:224
	v_mov_b32_e32 v149, v111
	v_mov_b32_e32 v132, v118
	v_mov_b32_e32 v119, v120
	s_waitcnt lgkmcnt(3)
	v_mfma_f32_32x32x16_bf16 v[0:15], v[48:51], v[24:27], v[0:15]
	ds_read_b128 v[24:27], v115
	v_lshlrev_b32_e32 v48, 16, v30
	v_and_b32_e32 v49, 0xffff0000, v30
	v_lshlrev_b32_e32 v50, 16, v31
	v_and_b32_e32 v51, 0xffff0000, v31
	s_waitcnt lgkmcnt(1)
	v_mfma_f32_32x32x16_bf16 v[0:15], v[52:55], v[20:23], v[0:15]
	v_lshlrev_b32_e32 v52, 16, v17
	v_and_b32_e32 v53, 0xffff0000, v17
	v_lshlrev_b32_e32 v54, 16, v18
	v_and_b32_e32 v55, 0xffff0000, v18
	ds_read_b128 v[16:19], v115 offset:32
	ds_read_b128 v[20:23], v115 offset:64
	s_waitcnt lgkmcnt(2)
	v_mfma_f32_32x32x16_bf16 v[0:15], v[24:27], v[36:39], v[0:15]
	v_mad_i32_i24 v24, v121, s38, v63
	v_add_u32_e32 v25, 0x2400, v24
	v_add_u32_e32 v26, 0x3000, v24
	v_add_u32_e32 v27, 0x3400, v24
	v_lshlrev_b64 v[36:37], 12, v[68:69]
	v_lshl_add_u64 v[36:37], s[90:91], 0, v[36:37]
	v_lshl_add_u64 v[36:37], v[36:37], 0, s[22:23]
	s_waitcnt lgkmcnt(1)
	v_mfma_f32_32x32x16_bf16 v[0:15], v[16:19], v[40:43], v[0:15]
	ds_read_b128 v[16:19], v115 offset:96
	v_lshl_add_u64 v[36:37], v[36:37], 0, v[56:57]
	v_mov_b32_e32 v115, v117
	v_mov_b32_e32 v121, v131
	s_waitcnt lgkmcnt(1)
	v_mfma_f32_32x32x16_bf16 v[0:15], v[20:23], v[32:35], v[0:15]
	v_add_u32_e32 v20, 0x400, v24
	v_add_u32_e32 v21, 0x1000, v24
	v_add_u32_e32 v22, 0x1400, v24
	v_add_u32_e32 v23, 0x2000, v24
	s_waitcnt lgkmcnt(0)
	v_mfma_f32_32x32x16_bf16 v[0:15], v[16:19], v[44:47], v[0:15]
	s_nop 11
	ds_write2_b32 v24, v0, v1 offset1:132
	ds_write2_b32 v20, v2, v3 offset0:8 offset1:140
	ds_write2_b32 v21, v4, v5 offset0:32 offset1:164
	ds_write2_b32 v22, v6, v7 offset0:40 offset1:172
	ds_write2_b32 v23, v8, v9 offset0:64 offset1:196
	ds_write2_b32 v25, v10, v11 offset0:72 offset1:204
	ds_write2_b32 v26, v12, v13 offset0:96 offset1:228
	ds_write2_b32 v27, v14, v15 offset0:104 offset1:236
	s_waitcnt lgkmcnt(0)
	s_barrier
; #define LAS __attribute__((address_space(3)))
; __device__ __forceinline__ unsigned pk2_rne(float lo, float hi) { const f32x2_t f = {lo, hi}; return __builtin_bit_cast(unsigned, __builtin_convertvector(f, bf16x2_t)); }
; __device__ __forceinline__ float bflo(unsigned w) { return __uint_as_float(w << 16); }
; __device__ __forceinline__ float bfhi(unsigned w) { return __uint_as_float(w & 0xffff0000u); }
; __device__ __forceinline__ void hgrn_c_load(Ctx& X, int u, RawC& R) {
;     const int hd = u & 7, c = u >> 3, t0 = c * 64, seg = X.tid >> 7, k = X.tid & 127;
;     const bf16_t* PR = (const bf16_t*)(X.ws + WS_PROJ);
;     const bf16_t* HQ = PR + 3 * TSZ; const bf16_t* HLF = PR + 4 * TSZ; const bf16_t* HV = PR + 5 * TSZ;
; #pragma unroll
;     for (int i = 0; i < 16; ++i) { const size_t off = (size_t)(t0 + 16 * seg + i) * 1024 + hd * 128 + k; R.lf[i] = HLF[off]; R.q[i] = HQ[off]; R.vv[i] = HV[off]; }
; }
; __device__ __forceinline__ void hgrn_c_compute(Ctx& X, int u, const RawC& R) {
;     ...
;     {
;         float ov[16]; float ss = 0.f;
; #pragma unroll
;         for (int e = 0; e < 4; ++e) { const f32x4 q4 = *(const LAS f32x4*)(OF + tn * 132 + 16 * sub + 4 * e); ov[4 * e] = q4[0]; ov[4 * e + 1] = q4[1]; ov[4 * e + 2] = q4[2]; ov[4 * e + 3] = q4[3]; }
; #pragma unroll
;         for (int e = 0; e < 16; ++e) ss += ov[e] * ov[e];
;         ss += __shfl_xor(ss, 1); ss += __shfl_xor(ss, 2); ss += __shfl_xor(ss, 4);
;         const float rinv = rsqrtf(ss * (1.f / 128.f) + EPS);
;         const unsigned gw[8] = {g0.x, g0.y, g0.z, g0.w, g1.x, g1.y, g1.z, g1.w};
;         unsigned pw[8];
; #pragma unroll
;         for (int e = 0; e < 8; ++e) {
;             const float w0 = X.gnorm_w[16 * sub + 2 * e], w1 = X.gnorm_w[16 * sub + 2 * e + 1];
;             pw[e] = pk2_rne(ov[2 * e] * rinv * w0 * bflo(gw[e]), ov[2 * e + 1] * rinv * w1 * bfhi(gw[e]));
;         }
;         bf16_t* yp = (bf16_t*)(X.ws + WS_H) + (size_t)(t0 + tn) * D + 1024 + hd * 128 + 16 * sub;
;         *(u32x4*)(yp) = (u32x4){pw[0], pw[1], pw[2], pw[3]}; *(u32x4*)(yp + 8) = (u32x4){pw[4], pw[5], pw[6], pw[7]};
;     }
	global_load_dwordx4 v[0:3], v[64:65], off offset:16
	global_load_dwordx4 v[4:7], v[64:65], off
	global_load_dwordx4 v[12:15], v[64:65], off offset:48
	global_load_dwordx4 v[16:19], v[64:65], off offset:32
	ds_read_b128 v[20:23], v97
	ds_read_b128 v[24:27], v97 offset:32
	ds_read_b128 v[28:31], v97 offset:48
	ds_read_b128 v[32:35], v97 offset:16
	v_mov_b32_e32 v11, v147
	v_mov_b32_e32 v10, v146
	s_waitcnt lgkmcnt(3)
	v_mul_f32_e32 v46, v21, v21
	v_fmac_f32_e32 v46, v20, v20
	v_fmac_f32_e32 v46, v22, v22
	v_fmac_f32_e32 v46, v23, v23
	s_waitcnt lgkmcnt(0)
	v_fmac_f32_e32 v46, v32, v32
	v_fmac_f32_e32 v46, v33, v33
	v_fmac_f32_e32 v46, v34, v34
	v_pk_mul_f32 v[40:41], v[24:25], v[24:25]
	v_fmac_f32_e32 v46, v35, v35
	v_add_f32_e32 v40, v40, v46
	v_pk_mul_f32 v[38:39], v[26:27], v[26:27]
	v_add_f32_e32 v40, v41, v40
	v_add_f32_e32 v38, v38, v40
	v_pk_mul_f32 v[44:45], v[28:29], v[28:29]
	v_add_f32_e32 v38, v39, v38
	v_add_f32_e32 v38, v44, v38
	v_pk_mul_f32 v[42:43], v[30:31], v[30:31]
	v_add_f32_e32 v38, v45, v38
	v_add_f32_e32 v38, v42, v38
	v_add_f32_e32 v38, v43, v38
	ds_bpermute_b32 v39, v98, v38
	v_mov_b32_e32 v9, v144
	v_mov_b32_e32 v8, v145
	s_waitcnt lgkmcnt(0)
	v_add_f32_e32 v38, v38, v39
	ds_bpermute_b32 v39, v99, v38
	s_waitcnt lgkmcnt(0)
	v_add_f32_e32 v40, v38, v39
	ds_bpermute_b32 v41, v100, v40
	v_lshl_add_u64 v[38:39], v[36:37], 0, s[30:31]
	v_add_co_u32_e32 v36, vcc, s41, v36
	s_waitcnt lgkmcnt(0)
	v_add_f32_e32 v40, v40, v41
	v_fmamk_f32 v40, v40, 0x3c000000, v104
	v_mul_f32_e32 v41, 0x4b800000, v40
	v_cmp_gt_f32_e64 s[10:11], s3, v40
	v_addc_co_u32_e32 v37, vcc, 0, v37, vcc
	s_nop 0
	v_cndmask_b32_e64 v40, v40, v41, s[10:11]
	v_rsq_f32_e32 v40, v40
	s_andn2_b64 vcc, exec, s[34:35]
	v_mul_f32_e32 v41, 0x45800000, v40
	v_cndmask_b32_e64 v40, v40, v41, s[10:11]
	v_pk_mul_f32 v[20:21], v[20:21], v[40:41] op_sel_hi:[1,0]
	v_pk_mul_f32 v[22:23], v[22:23], v[40:41] op_sel_hi:[1,0]
	v_pk_mul_f32 v[32:33], v[32:33], v[40:41] op_sel_hi:[1,0]
	v_pk_mul_f32 v[34:35], v[34:35], v[40:41] op_sel_hi:[1,0]
	v_pk_mul_f32 v[24:25], v[24:25], v[40:41] op_sel_hi:[1,0]
	v_pk_mul_f32 v[26:27], v[26:27], v[40:41] op_sel_hi:[1,0]
	v_pk_mul_f32 v[28:29], v[28:29], v[40:41] op_sel_hi:[1,0]
	v_pk_mul_f32 v[30:31], v[30:31], v[40:41] op_sel_hi:[1,0]
	s_waitcnt vmcnt(3)
	v_pk_mul_f32 v[0:1], v[0:1], v[32:33]
	s_waitcnt vmcnt(2)
	v_pk_mul_f32 v[4:5], v[4:5], v[20:21]
	v_pk_mul_f32 v[6:7], v[6:7], v[22:23]
	v_pk_mul_f32 v[2:3], v[2:3], v[34:35]
	s_waitcnt vmcnt(0)
	v_pk_mul_f32 v[16:17], v[16:17], v[24:25]
	v_pk_mul_f32 v[18:19], v[18:19], v[26:27]
	v_pk_mul_f32 v[12:13], v[12:13], v[28:29]
	v_pk_mul_f32 v[14:15], v[14:15], v[30:31]
	v_pk_mul_f32 v[4:5], v[4:5], v[170:171]
	v_pk_mul_f32 v[6:7], v[6:7], v[172:173]
	v_pk_mul_f32 v[20:21], v[0:1], v[48:49]
	v_pk_mul_f32 v[22:23], v[2:3], v[50:51]
	v_pk_mul_f32 v[16:17], v[16:17], v[174:175]
	v_pk_mul_f32 v[18:19], v[18:19], v[52:53]
	v_pk_mul_f32 v[12:13], v[12:13], v[54:55]
	v_pk_mul_f32 v[14:15], v[14:15], v[176:177]
	v_cvt_pk_bf16_f32 v0, v4, v5
	v_cvt_pk_bf16_f32 v1, v6, v7
	v_cvt_pk_bf16_f32 v2, v20, v21
	v_cvt_pk_bf16_f32 v3, v22, v23
	v_cvt_pk_bf16_f32 v4, v16, v17
	v_cvt_pk_bf16_f32 v5, v18, v19
	v_cvt_pk_bf16_f32 v6, v12, v13
	v_cvt_pk_bf16_f32 v7, v14, v15
	global_store_dwordx4 v[36:37], v[0:3], off offset:2048
	global_store_dwordx4 v[38:39], v[4:7], off offset:16
	v_mov_b32_e32 v15, v130
	v_mov_b32_e32 v14, v125
	v_mov_b32_e32 v13, v126
	v_mov_b32_e32 v12, v127
	s_waitcnt vmcnt(2)
	v_perm_b32 v140, v214, v213, s39
	v_perm_b32 v141, v216, v215, s39
	v_perm_b32 v142, v218, v217, s39
	v_perm_b32 v143, v220, v219, s39
	v_perm_b32 v133, v222, v221, s39
	v_perm_b32 v134, v224, v223, s39
	v_perm_b32 v135, v211, v225, s39
	v_perm_b32 v136, v210, v212, s39
	v_mov_b32_e32 v0, v140
	v_mov_b32_e32 v1, v141
	v_mov_b32_e32 v2, v142
	v_mov_b32_e32 v3, v143
	v_mov_b32_e32 v4, v133
	v_mov_b32_e32 v5, v134
	v_mov_b32_e32 v6, v135
	v_mov_b32_e32 v7, v136
	s_barrier
	s_cbranch_vccz .LBB0_739
.LBB0_733:
	s_add_i32 s42, s42, s94
	s_cmpk_gt_i32 s42, 0x7ff
	s_cselect_b64 s[34:35], -1, 0
	s_and_b64 vcc, exec, s[34:35]
	s_cbranch_vccnz .LBB0_735
	s_add_i32 s2, s50, s54
	s_andn2_b32 s2, s2, 63
	v_add_u32_e32 v226, s2, v71
	s_add_i32 s2, s40, s36
	s_and_b32 s2, s2, 0x380
	v_or_b32_e32 v227, s2, v59
	v_lshlrev_b32_e32 v227, 1, v227
	v_lshl_or_b32 v226, v226, 11, v227
	v_add_u32_e32 v228, 0x1000, v226
	v_add_u32_e32 v229, 0x2000, v226
	v_add_u32_e32 v230, 0x3000, v226
	v_add_u32_e32 v231, 0x4000, v226
	v_add_u32_e32 v232, 0x5000, v226
	v_add_u32_e32 v233, 0x6000, v226
	v_add_u32_e32 v234, 0x7000, v226
	s_branch .LBB0_736

; __device__ __forceinline__ unsigned pk2_rne(float lo, float hi) { const f32x2_t f = {lo, hi}; return __builtin_bit_cast(unsigned, __builtin_convertvector(f, bf16x2_t)); }
; __device__ __forceinline__ float bf2f(unsigned short b) { return __uint_as_float(((unsigned)b) << 16); }
; __device__ __forceinline__ void hgrn_c_compute(Ctx& X, int u, const RawC& R) {
;     ...
;         float lf[16], b[16]; float run = 0.f;
; #pragma unroll
;         for (int i = 0; i < 16; ++i) { lf[i] = bf2f(R.lf[i]); run += lf[i]; b[i] = run; }
;         SEG[seg * 128 + k] = run;
;         __syncthreads();
;         float off = 0.f;
; #pragma unroll
;         for (int s = 0; s < 4; ++s) { const float v = SEG[s * 128 + k]; off += (s < seg) ? v : 0.f; }
;         const float bmid = SEG[k] + SEG[128 + k];
;         unsigned pv[8];
; #pragma unroll
;         for (int i = 0; i < 16; ++i) {
;             const float bt = off + b[i]; const int t = 16 * seg + i; const float q = bf2f(R.q[i]);
;             const unsigned qh = pk2_rne(q * __expf(bt), q * __expf(bt - bmid));
;             const unsigned kk = pk2_rne((1.f - __expf(lf[i])) * __expf(bmid - bt), 0.f);
;             QH[t * 136 + k] = (bf16_t)(qh & 0xffffu); QT[t * 136 + k] = (bf16_t)(qh >> 16); KT2[t * 136 + k] = (bf16_t)(kk & 0xffffu);
;         }
.LBB0_736:
	v_lshlrev_b32_e32 v170, 16, v168
	v_add_f32_e32 v168, 0, v170
	v_lshlrev_b32_e32 v167, 16, v167
	v_add_f32_e32 v171, v168, v167
	v_lshlrev_b32_e32 v166, 16, v166
	v_add_f32_e32 v172, v171, v166
	v_lshlrev_b32_e32 v165, 16, v165
	v_add_f32_e32 v173, v172, v165
	v_lshlrev_b32_e32 v161, 16, v161
	v_add_f32_e32 v174, v173, v161
	v_lshlrev_b32_e32 v160, 16, v160
	v_add_f32_e32 v175, v174, v160
	v_lshlrev_b32_e32 v163, 16, v163
	v_add_f32_e32 v176, v175, v163
	v_lshlrev_b32_e32 v162, 16, v162
	v_add_f32_e32 v177, v176, v162
	v_lshlrev_b32_e32 v156, 16, v156
	v_add_f32_e32 v178, v177, v156
	v_lshlrev_b32_e32 v179, 16, v155
	s_and_b32 s2, s54, 0xffffffc0
	v_add_f32_e32 v180, v178, v179
	v_lshlrev_b32_e32 v181, 16, v154
	v_add_u32_e32 v68, s2, v70
	v_add_f32_e32 v182, v180, v181
	v_lshlrev_b32_e32 v183, 16, v152
	v_ashrrev_i32_e32 v69, 31, v68
	v_add_f32_e32 v184, v182, v183
	v_lshlrev_b32_e32 v185, 16, v11
	v_lshlrev_b64 v[16:17], 11, v[68:69]
	s_and_b32 s2, s36, 0x380
	v_add_f32_e32 v186, v184, v185
	v_lshlrev_b32_e32 v187, 16, v10
	v_lshl_add_u64 v[16:17], s[20:21], 0, v[16:17]
	s_lshl_b32 s22, s2, 1
	v_add_f32_e32 v188, v186, v187
	v_lshlrev_b32_e32 v189, 16, v9
	v_lshl_add_u64 v[16:17], v[16:17], 0, s[22:23]
	v_add_f32_e32 v190, v188, v189
	v_lshlrev_b32_e32 v192, 16, v8
	v_lshl_add_u64 v[28:29], v[16:17], 0, v[56:57]
	v_add_f32_e32 v193, v190, v192
	s_mov_b32 m0, s72
	v_lshl_add_u64 v[204:205], v[66:67], 0, v[194:195]
	global_load_lds_dwordx4 v[204:205], off
	s_add_i32 m0, s72, 0x400
	v_lshl_add_u64 v[204:205], v[66:67], 0, v[196:197]
	global_load_lds_dwordx4 v[204:205], off
	s_add_i32 m0, s72, 0x800
	v_lshl_add_u64 v[204:205], v[66:67], 0, v[198:199]
	global_load_lds_dwordx4 v[204:205], off
	s_add_i32 m0, s72, 0xc00
	v_lshl_add_u64 v[204:205], v[66:67], 0, v[200:201]
	global_load_lds_dwordx4 v[204:205], off
	global_load_dwordx4 v[16:19], v[28:29], off offset:16
	s_nop 0
	global_load_dwordx4 v[28:31], v[28:29], off
	ds_write_b32 v73, v193
	s_waitcnt lgkmcnt(0)
	s_barrier
	ds_read2st64_b32 v[8:9], v74 offset1:2
	ds_read2st64_b32 v[10:11], v74 offset0:4 offset1:6
	s_andn2_b64 vcc, exec, s[24:25]
	global_load_ushort v114, v226, s[16:17]
	s_mov_b32 s2, s37
	s_waitcnt lgkmcnt(1)
	v_add_f32_e32 v152, 0, v8
	v_cndmask_b32_e64 v152, v152, 0, s[0:1]
	v_cndmask_b32_e64 v154, 0, v9, s[4:5]
	v_add_f32_e32 v152, v152, v154
	s_waitcnt lgkmcnt(0)
	global_load_ushort v105, v226, s[14:15]
	v_cndmask_b32_e64 v10, 0, v10, s[6:7]
	v_add_f32_e32 v10, v152, v10
	v_cndmask_b32_e64 v11, 0, v11, s[8:9]
	v_add_f32_e32 v10, v10, v11
	v_mov_b32_e32 v169, v8
	v_mov_b32_e32 v11, v9
	v_pk_add_f32 v[8:9], v[168:169], v[10:11]
	global_load_ushort v213, v226, s[18:19]
	v_lshlrev_b32_e32 v152, 16, v164
	v_mul_f32_e32 v11, 0x3fb8aa3b, v8
	v_exp_f32_e32 v154, v11
	v_sub_f32_e32 v11, v8, v9
	v_mul_f32_e32 v11, 0x3fb8aa3b, v11
	v_exp_f32_e32 v155, v11
	v_mul_f32_e32 v11, 0x3fb8aa3b, v170
	global_load_ushort v112, v226, s[16:17] offset:2048
	v_sub_f32_e32 v8, v9, v8
	v_exp_f32_e32 v11, v11
	v_mul_f32_e32 v8, 0x3fb8aa3b, v8
	v_exp_f32_e32 v8, v8
	v_pk_mul_f32 v[154:155], v[154:155], v[152:153] op_sel_hi:[1,0]
	v_sub_f32_e32 v11, 1.0, v11
	v_cvt_pk_bf16_f32 v152, v154, v155
	global_load_ushort v106, v226, s[14:15] offset:2048
	v_mul_f32_e32 v8, v11, v8
	v_add_f32_e32 v11, v171, v10
	v_cvt_pk_bf16_f32 v8, v8, s0
	ds_write_b16 v75, v152
	ds_write_b16_d16_hi v75, v152 offset:17408
	ds_write_b16 v75, v8 offset:34816
	v_mul_f32_e32 v152, 0x3fb8aa3b, v11
	global_load_ushort v214, v226, s[18:19] offset:2048
	v_exp_f32_e32 v154, v152
	v_sub_f32_e32 v152, v11, v9
	v_mul_f32_e32 v152, 0x3fb8aa3b, v152
	v_exp_f32_e32 v155, v152
	v_mul_f32_e32 v152, 0x3fb8aa3b, v167
	v_sub_f32_e32 v11, v9, v11
	v_exp_f32_e32 v152, v152
	global_load_ushort v113, v228, s[16:17]
	v_mul_f32_e32 v11, 0x3fb8aa3b, v11
	v_exp_f32_e32 v11, v11
	v_lshlrev_b32_e32 v8, 16, v159
	v_sub_f32_e32 v152, 1.0, v152
	v_pk_mul_f32 v[154:155], v[154:155], v[8:9] op_sel_hi:[1,0]
	v_mul_f32_e32 v11, v152, v11
	v_cvt_pk_bf16_f32 v8, v154, v155
	global_load_ushort v107, v228, s[14:15]
	v_cvt_pk_bf16_f32 v11, v11, s0
	ds_write_b16 v75, v8 offset:272
	ds_write_b16_d16_hi v75, v8 offset:17680
	ds_write_b16 v75, v11 offset:35088
	v_add_f32_e32 v11, v172, v10
	v_mul_f32_e32 v152, 0x3fb8aa3b, v11
	v_exp_f32_e32 v154, v152
	global_load_ushort v215, v228, s[18:19]
	v_sub_f32_e32 v152, v11, v9
	v_mul_f32_e32 v152, 0x3fb8aa3b, v152
	v_exp_f32_e32 v155, v152
	v_mul_f32_e32 v152, 0x3fb8aa3b, v166
	v_sub_f32_e32 v11, v9, v11
	v_exp_f32_e32 v152, v152
	v_mul_f32_e32 v11, 0x3fb8aa3b, v11
	global_load_ushort v122, v228, s[16:17] offset:2048
	v_exp_f32_e32 v11, v11
	v_lshlrev_b32_e32 v8, 16, v158
	v_sub_f32_e32 v152, 1.0, v152
	v_pk_mul_f32 v[154:155], v[154:155], v[8:9] op_sel_hi:[1,0]
	v_mul_f32_e32 v11, v152, v11
	v_cvt_pk_bf16_f32 v8, v154, v155
	v_cvt_pk_bf16_f32 v11, v11, s0
	global_load_ushort v108, v228, s[14:15] offset:2048
	ds_write_b16 v75, v8 offset:544
	ds_write_b16_d16_hi v75, v8 offset:17952
	ds_write_b16 v75, v11 offset:35360
	v_add_f32_e32 v11, v173, v10
	v_mul_f32_e32 v152, 0x3fb8aa3b, v11
	v_exp_f32_e32 v154, v152
	v_sub_f32_e32 v152, v11, v9
	global_load_ushort v216, v228, s[18:19] offset:2048
	v_mul_f32_e32 v152, 0x3fb8aa3b, v152
	v_exp_f32_e32 v155, v152
	v_mul_f32_e32 v152, 0x3fb8aa3b, v165
	v_sub_f32_e32 v11, v9, v11
	v_exp_f32_e32 v152, v152
	v_mul_f32_e32 v11, 0x3fb8aa3b, v11
	v_exp_f32_e32 v11, v11
	global_load_ushort v123, v229, s[16:17]
	v_lshlrev_b32_e32 v8, 16, v157
	v_sub_f32_e32 v152, 1.0, v152
	v_pk_mul_f32 v[154:155], v[154:155], v[8:9] op_sel_hi:[1,0]
	v_mul_f32_e32 v11, v152, v11
	v_cvt_pk_bf16_f32 v8, v154, v155
; __device__ __forceinline__ unsigned pk2_rne(float lo, float hi) { const f32x2_t f = {lo, hi}; return __builtin_bit_cast(unsigned, __builtin_convertvector(f, bf16x2_t)); }
; __device__ __forceinline__ float bf2f(unsigned short b) { return __uint_as_float(((unsigned)b) << 16); }
; __device__ __forceinline__ void hgrn_c_compute(Ctx& X, int u, const RawC& R) {
;     ...
;         for (int i = 0; i < 16; ++i) {
;             const float bt = off + b[i]; const int t = 16 * seg + i; const float q = bf2f(R.q[i]);
;             const unsigned qh = pk2_rne(q * __expf(bt), q * __expf(bt - bmid));
;             const unsigned kk = pk2_rne((1.f - __expf(lf[i])) * __expf(bmid - bt), 0.f);
;             QH[t * 136 + k] = (bf16_t)(qh & 0xffffu); QT[t * 136 + k] = (bf16_t)(qh >> 16); KT2[t * 136 + k] = (bf16_t)(kk & 0xffffu);
;         }
	v_cvt_pk_bf16_f32 v11, v11, s0
	ds_write_b16 v75, v8 offset:816
	global_load_ushort v109, v229, s[14:15]
	ds_write_b16_d16_hi v75, v8 offset:18224
	ds_write_b16 v75, v11 offset:35632
	v_add_f32_e32 v11, v174, v10
	v_lshlrev_b32_e32 v8, 16, v153
	v_sub_f32_e32 v153, v11, v9
	v_mul_f32_e32 v152, 0x3fb8aa3b, v11
	v_mul_f32_e32 v153, 0x3fb8aa3b, v153
	global_load_ushort v217, v229, s[18:19]
	v_exp_f32_e32 v152, v152
	v_exp_f32_e32 v153, v153
	v_mul_f32_e32 v154, 0x3fb8aa3b, v161
	v_sub_f32_e32 v11, v9, v11
	v_exp_f32_e32 v154, v154
	v_mul_f32_e32 v11, 0x3fb8aa3b, v11
	v_exp_f32_e32 v11, v11
	global_load_ushort v124, v229, s[16:17] offset:2048
	v_pk_mul_f32 v[152:153], v[152:153], v[8:9] op_sel_hi:[1,0]
	s_nop 0
	v_cvt_pk_bf16_f32 v8, v152, v153
	v_sub_f32_e32 v152, 1.0, v154
	v_mul_f32_e32 v11, v152, v11
	v_cvt_pk_bf16_f32 v11, v11, s0
	ds_write_b16 v75, v8 offset:1088
	global_load_ushort v116, v229, s[14:15] offset:2048
	ds_write_b16_d16_hi v75, v8 offset:18496
	ds_write_b16 v75, v11 offset:35904
	v_add_f32_e32 v11, v175, v10
	v_lshlrev_b32_e32 v8, 16, v151
	v_mul_f32_e32 v151, 0x3fb8aa3b, v11
	v_exp_f32_e32 v152, v151
	v_sub_f32_e32 v151, v11, v9
	global_load_ushort v218, v229, s[18:19] offset:2048
	v_mul_f32_e32 v151, 0x3fb8aa3b, v151
	v_exp_f32_e32 v153, v151
	v_mul_f32_e32 v151, 0x3fb8aa3b, v160
	v_sub_f32_e32 v11, v9, v11
	v_exp_f32_e32 v151, v151
	v_mul_f32_e32 v11, 0x3fb8aa3b, v11
	v_exp_f32_e32 v11, v11
	global_load_ushort v128, v230, s[16:17]
	v_pk_mul_f32 v[152:153], v[152:153], v[8:9] op_sel_hi:[1,0]
	v_sub_f32_e32 v151, 1.0, v151
	v_cvt_pk_bf16_f32 v8, v152, v153
	v_mul_f32_e32 v11, v151, v11
	v_cvt_pk_bf16_f32 v11, v11, s0
	ds_write_b16 v75, v8 offset:1360
	ds_write_b16_d16_hi v75, v8 offset:18768
	global_load_ushort v110, v230, s[14:15]
	ds_write_b16 v75, v11 offset:36176
	v_add_f32_e32 v11, v176, v10
	v_sub_f32_e32 v151, v11, v9
	v_lshlrev_b32_e32 v8, 16, v150
	v_mul_f32_e32 v150, 0x3fb8aa3b, v11
	v_mul_f32_e32 v151, 0x3fb8aa3b, v151
	v_exp_f32_e32 v150, v150
	global_load_ushort v219, v230, s[18:19]
	v_exp_f32_e32 v151, v151
	v_mul_f32_e32 v152, 0x3fb8aa3b, v163
	v_sub_f32_e32 v11, v9, v11
	v_exp_f32_e32 v152, v152
	v_mul_f32_e32 v11, 0x3fb8aa3b, v11
	v_exp_f32_e32 v11, v11
	v_pk_mul_f32 v[150:151], v[150:151], v[8:9] op_sel_hi:[1,0]
	global_load_ushort v129, v230, s[16:17] offset:2048
	s_nop 0
	v_cvt_pk_bf16_f32 v8, v150, v151
	v_sub_f32_e32 v150, 1.0, v152
	v_mul_f32_e32 v11, v150, v11
	v_cvt_pk_bf16_f32 v11, v11, s0
	ds_write_b16 v75, v8 offset:1632
	ds_write_b16_d16_hi v75, v8 offset:19040
	global_load_ushort v111, v230, s[14:15] offset:2048
	ds_write_b16 v75, v11 offset:36448
	v_add_f32_e32 v11, v177, v10
	v_lshlrev_b32_e32 v8, 16, v149
	v_mul_f32_e32 v149, 0x3fb8aa3b, v11
	v_exp_f32_e32 v150, v149
	v_sub_f32_e32 v149, v11, v9
	v_mul_f32_e32 v149, 0x3fb8aa3b, v149
	global_load_ushort v220, v230, s[18:19] offset:2048
	v_exp_f32_e32 v151, v149
	v_mul_f32_e32 v149, 0x3fb8aa3b, v162
	v_sub_f32_e32 v11, v9, v11
	v_exp_f32_e32 v149, v149
	v_mul_f32_e32 v11, 0x3fb8aa3b, v11
	v_exp_f32_e32 v11, v11
	v_pk_mul_f32 v[150:151], v[150:151], v[8:9] op_sel_hi:[1,0]
	global_load_ushort v137, v231, s[16:17]
	v_sub_f32_e32 v149, 1.0, v149
	v_cvt_pk_bf16_f32 v8, v150, v151
	v_mul_f32_e32 v11, v149, v11
	v_cvt_pk_bf16_f32 v11, v11, s0
	ds_write_b16 v75, v8 offset:1904
	ds_write_b16_d16_hi v75, v8 offset:19312
	ds_write_b16 v75, v11 offset:36720
	global_load_ushort v118, v231, s[14:15]
	v_add_f32_e32 v11, v178, v10
	v_lshlrev_b32_e32 v8, 16, v132
	v_mul_f32_e32 v132, 0x3fb8aa3b, v11
	v_exp_f32_e32 v150, v132
	v_sub_f32_e32 v132, v11, v9
	v_mul_f32_e32 v132, 0x3fb8aa3b, v132
	v_exp_f32_e32 v151, v132
	global_load_ushort v221, v231, s[18:19]
	v_mul_f32_e32 v132, 0x3fb8aa3b, v156
	v_sub_f32_e32 v11, v9, v11
	v_exp_f32_e32 v132, v132
	v_mul_f32_e32 v11, 0x3fb8aa3b, v11
	v_exp_f32_e32 v11, v11
	v_pk_mul_f32 v[150:151], v[150:151], v[8:9] op_sel_hi:[1,0]
	v_sub_f32_e32 v132, 1.0, v132
	global_load_ushort v138, v231, s[16:17] offset:2048
	v_cvt_pk_bf16_f32 v8, v150, v151
	v_mul_f32_e32 v11, v132, v11
	v_cvt_pk_bf16_f32 v11, v11, s0
	ds_write_b16 v75, v8 offset:2176
	ds_write_b16_d16_hi v75, v8 offset:19584
	ds_write_b16 v75, v11 offset:36992
	v_add_f32_e32 v11, v180, v10
	global_load_ushort v120, v231, s[14:15] offset:2048
	v_lshlrev_b32_e32 v8, 16, v119
	v_mul_f32_e32 v119, 0x3fb8aa3b, v11
	v_exp_f32_e32 v150, v119
	v_sub_f32_e32 v119, v11, v9
	v_mul_f32_e32 v119, 0x3fb8aa3b, v119
	v_exp_f32_e32 v151, v119
	v_mul_f32_e32 v119, 0x3fb8aa3b, v179
	global_load_ushort v222, v231, s[18:19] offset:2048
	v_sub_f32_e32 v11, v9, v11
	v_exp_f32_e32 v119, v119
	v_mul_f32_e32 v11, 0x3fb8aa3b, v11
	v_exp_f32_e32 v11, v11
	v_pk_mul_f32 v[150:151], v[150:151], v[8:9] op_sel_hi:[1,0]
	v_sub_f32_e32 v119, 1.0, v119
	v_cvt_pk_bf16_f32 v8, v150, v151
	global_load_ushort v139, v232, s[16:17]
	v_mul_f32_e32 v11, v119, v11
	v_cvt_pk_bf16_f32 v11, v11, s0
	ds_write_b16 v75, v8 offset:2448
	ds_write_b16_d16_hi v75, v8 offset:19856
	ds_write_b16 v75, v11 offset:37264
	v_add_f32_e32 v11, v182, v10
	v_lshlrev_b32_e32 v8, 16, v115
	global_load_ushort v117, v232, s[14:15]
	v_mul_f32_e32 v115, 0x3fb8aa3b, v11
	v_exp_f32_e32 v150, v115
	v_sub_f32_e32 v115, v11, v9
; #define LAS __attribute__((address_space(3)))
; __device__ __forceinline__ unsigned pk2_rne(float lo, float hi) { const f32x2_t f = {lo, hi}; return __builtin_bit_cast(unsigned, __builtin_convertvector(f, bf16x2_t)); }
; __device__ __forceinline__ float bf2f(unsigned short b) { return __uint_as_float(((unsigned)b) << 16); }
; __device__ __forceinline__ void hgrn_c_compute(Ctx& X, int u, const RawC& R) {
;     ...
;         for (int i = 0; i < 16; ++i) {
;             const float bt = off + b[i]; const int t = 16 * seg + i; const float q = bf2f(R.q[i]);
;             const unsigned qh = pk2_rne(q * __expf(bt), q * __expf(bt - bmid));
;             const unsigned kk = pk2_rne((1.f - __expf(lf[i])) * __expf(bmid - bt), 0.f);
;             QH[t * 136 + k] = (bf16_t)(qh & 0xffffu); QT[t * 136 + k] = (bf16_t)(qh >> 16); KT2[t * 136 + k] = (bf16_t)(kk & 0xffffu);
;         }
; #pragma unroll
;         for (int i = 0; i < 8; ++i) pv[i] = (unsigned)R.vv[2 * i] | ((unsigned)R.vv[2 * i + 1] << 16);
;         *(LAS u32x4*)(VT + k * 72 + 16 * seg) = (u32x4){pv[0], pv[1], pv[2], pv[3]}; *(LAS u32x4*)(VT + k * 72 + 16 * seg + 8) = (u32x4){pv[4], pv[5], pv[6], pv[7]};
;     }
;     __syncthreads();
	v_mul_f32_e32 v115, 0x3fb8aa3b, v115
	v_exp_f32_e32 v151, v115
	v_mul_f32_e32 v115, 0x3fb8aa3b, v181
	v_sub_f32_e32 v11, v9, v11
	global_load_ushort v223, v232, s[18:19]
	v_exp_f32_e32 v115, v115
	v_mul_f32_e32 v11, 0x3fb8aa3b, v11
	v_exp_f32_e32 v11, v11
	v_pk_mul_f32 v[150:151], v[150:151], v[8:9] op_sel_hi:[1,0]
	v_sub_f32_e32 v115, 1.0, v115
	v_cvt_pk_bf16_f32 v8, v150, v151
	v_mul_f32_e32 v11, v115, v11
	global_load_ushort v224, v232, s[18:19] offset:2048
	v_cvt_pk_bf16_f32 v11, v11, s0
	ds_write_b16 v75, v8 offset:2720
	ds_write_b16_d16_hi v75, v8 offset:20128
	ds_write_b16 v75, v11 offset:37536
	v_add_f32_e32 v11, v184, v10
	v_mul_f32_e32 v115, 0x3fb8aa3b, v11
	v_exp_f32_e32 v150, v115
	global_load_ushort v225, v233, s[18:19]
	v_sub_f32_e32 v115, v11, v9
	v_mul_f32_e32 v115, 0x3fb8aa3b, v115
	v_exp_f32_e32 v151, v115
	v_mul_f32_e32 v115, 0x3fb8aa3b, v183
	v_sub_f32_e32 v11, v9, v11
	v_exp_f32_e32 v115, v115
	v_mul_f32_e32 v11, 0x3fb8aa3b, v11
	global_load_ushort v125, v233, s[14:15] offset:2048
	v_exp_f32_e32 v11, v11
	v_lshlrev_b32_e32 v8, 16, v121
	v_sub_f32_e32 v115, 1.0, v115
	v_pk_mul_f32 v[150:151], v[150:151], v[8:9] op_sel_hi:[1,0]
	v_mul_f32_e32 v11, v115, v11
	v_cvt_pk_bf16_f32 v8, v150, v151
	v_cvt_pk_bf16_f32 v11, v11, s0
	global_load_ushort v211, v233, s[18:19] offset:2048
	ds_write_b16 v75, v8 offset:2992
	ds_write_b16_d16_hi v75, v8 offset:20400
	ds_write_b16 v75, v11 offset:37808
	v_add_f32_e32 v11, v186, v10
	v_lshlrev_b32_e32 v8, 16, v15
	v_mul_f32_e32 v15, 0x3fb8aa3b, v11
	v_exp_f32_e32 v150, v15
	global_load_ushort v144, v234, s[16:17]
	v_sub_f32_e32 v15, v11, v9
	v_mul_f32_e32 v15, 0x3fb8aa3b, v15
	v_exp_f32_e32 v151, v15
	v_mul_f32_e32 v15, 0x3fb8aa3b, v185
	v_sub_f32_e32 v11, v9, v11
	v_exp_f32_e32 v15, v15
	v_mul_f32_e32 v11, 0x3fb8aa3b, v11
	global_load_ushort v126, v234, s[14:15]
	v_exp_f32_e32 v11, v11
	v_pk_mul_f32 v[150:151], v[150:151], v[8:9] op_sel_hi:[1,0]
	v_sub_f32_e32 v15, 1.0, v15
	v_cvt_pk_bf16_f32 v8, v150, v151
	v_mul_f32_e32 v11, v15, v11
	v_cvt_pk_bf16_f32 v11, v11, s0
	ds_write_b16 v75, v8 offset:3264
	global_load_ushort v212, v234, s[18:19]
	ds_write_b16_d16_hi v75, v8 offset:20672
	ds_write_b16 v75, v11 offset:38080
	v_add_f32_e32 v11, v188, v10
	v_sub_f32_e32 v15, v11, v9
	v_lshlrev_b32_e32 v8, 16, v14
	v_mul_f32_e32 v14, 0x3fb8aa3b, v11
	v_mul_f32_e32 v15, 0x3fb8aa3b, v15
	global_load_ushort v145, v234, s[16:17] offset:2048
	v_exp_f32_e32 v14, v14
	v_exp_f32_e32 v15, v15
	v_mul_f32_e32 v115, 0x3fb8aa3b, v187
	v_sub_f32_e32 v11, v9, v11
	v_exp_f32_e32 v115, v115
	v_mul_f32_e32 v11, 0x3fb8aa3b, v11
	v_exp_f32_e32 v11, v11
	global_load_ushort v127, v234, s[14:15] offset:2048
	v_pk_mul_f32 v[14:15], v[14:15], v[8:9] op_sel_hi:[1,0]
	v_mov_b32_e32 v119, v61
	v_cvt_pk_bf16_f32 v8, v14, v15
	v_sub_f32_e32 v14, 1.0, v115
	v_mul_f32_e32 v11, v14, v11
	v_cvt_pk_bf16_f32 v11, v11, s0
	ds_write_b16 v75, v8 offset:3536
	global_load_ushort v210, v234, s[18:19] offset:2048
	ds_write_b16_d16_hi v75, v8 offset:20944
	ds_write_b16 v75, v11 offset:38352
	v_add_f32_e32 v11, v190, v10
	v_lshlrev_b32_e32 v8, 16, v13
	v_mul_f32_e32 v13, 0x3fb8aa3b, v11
	v_exp_f32_e32 v14, v13
	v_sub_f32_e32 v13, v11, v9
	global_load_ushort v148, v232, s[16:17] offset:2048
	v_mul_f32_e32 v13, 0x3fb8aa3b, v13
	v_exp_f32_e32 v15, v13
	v_mul_f32_e32 v13, 0x3fb8aa3b, v189
	v_sub_f32_e32 v11, v9, v11
	v_exp_f32_e32 v13, v13
	v_mul_f32_e32 v11, 0x3fb8aa3b, v11
	v_exp_f32_e32 v11, v11
	global_load_ushort v131, v232, s[14:15] offset:2048
	v_pk_mul_f32 v[14:15], v[14:15], v[8:9] op_sel_hi:[1,0]
	v_sub_f32_e32 v13, 1.0, v13
	v_cvt_pk_bf16_f32 v8, v14, v15
	v_mul_f32_e32 v11, v13, v11
	v_cvt_pk_bf16_f32 v11, v11, s0
	v_add_f32_e32 v13, v193, v10
	ds_write_b16 v75, v8 offset:3808
	global_load_ushort v147, v233, s[16:17]
	ds_write_b16_d16_hi v75, v8 offset:21216
	ds_write_b16 v75, v11 offset:38624
	v_sub_f32_e32 v11, v13, v9
	v_mul_f32_e32 v10, 0x3fb8aa3b, v13
	v_mul_f32_e32 v11, 0x3fb8aa3b, v11
	v_lshlrev_b32_e32 v8, 16, v12
	v_exp_f32_e32 v10, v10
	global_load_ushort v130, v233, s[14:15]
	v_exp_f32_e32 v11, v11
	v_mul_f32_e32 v12, 0x3fb8aa3b, v192
	v_sub_f32_e32 v9, v9, v13
	v_exp_f32_e32 v12, v12
	v_mul_f32_e32 v9, 0x3fb8aa3b, v9
	v_exp_f32_e32 v13, v9
	v_pk_mul_f32 v[8:9], v[10:11], v[8:9] op_sel_hi:[1,0]
	global_load_ushort v146, v233, s[16:17] offset:2048
	v_mov_b32_e32 v115, v77
	v_cvt_pk_bf16_f32 v8, v8, v9
	v_sub_f32_e32 v9, 1.0, v12
	v_mul_f32_e32 v9, v9, v13
	v_cvt_pk_bf16_f32 v9, v9, s0
	ds_write_b16 v75, v8 offset:4080
	ds_write_b16_d16_hi v75, v8 offset:21488
	ds_write_b16 v75, v9 offset:38896
	ds_write_b128 v103, v[0:3] offset:52224
	ds_write_b128 v103, v[4:7] offset:52240
	s_waitcnt lgkmcnt(0)
	s_barrier
	s_cbranch_vccnz .LBB0_732
	s_andn2_b64 vcc, exec, s[26:27]
	s_cbranch_vccz .LBB0_730
	v_mov_b32_e32 v0, 0
	s_mov_b32 s2, 0
	v_mov_b32_e32 v119, v102
	v_mov_b32_e32 v115, v101
	v_mov_b32_e32 v121, v72
	v_mov_b32_e32 v1, 0
	v_mov_b32_e32 v2, 0
	v_mov_b32_e32 v3, 0
	v_mov_b32_e32 v4, 0
	v_mov_b32_e32 v5, 0
	v_mov_b32_e32 v6, 0
	v_mov_b32_e32 v7, 0
	v_mov_b32_e32 v8, 0
	v_mov_b32_e32 v9, 0
	v_mov_b32_e32 v10, 0
	v_mov_b32_e32 v11, 0
	v_mov_b32_e32 v12, 0
	v_mov_b32_e32 v13, 0
	v_mov_b32_e32 v14, 0
	v_mov_b32_e32 v15, 0
	s_branch .LBB0_731
